# baseline (speedup 1.0000x reference)
; #define LAS __attribute__((address_space(3)))
; __device__ __forceinline__ unsigned pk2(float lo, float hi) { return f2bf(lo) | (f2bf(hi) << 16); }
; template <int KIND, int MODE>
; __device__ __forceinline__ void scan_unit(Frame& F, int layer, int h, int vhalf, int grp) {
;     ...
; #pragma unroll
;             for (int i = 0; i < 4; ++i) { const int c = tid + 512 * i, t = c >> 5, dc = (c & 31) * 8; const float wa = X[192 + t];
;                 const u32x4 k = pk[i]; u32x4 ko;
;                 if (MODE == 1) { const u32x4 q = qr[i]; u32x4 qo; qo.x = pk2(bflo(q.x) * 0.0625f, bfhi(q.x) * 0.0625f); qo.y = pk2(bflo(q.y) * 0.0625f, bfhi(q.y) * 0.0625f); qo.z = pk2(bflo(q.z) * 0.0625f, bfhi(q.z) * 0.0625f); qo.w = pk2(bflo(q.w) * 0.0625f, bfhi(q.w) * 0.0625f);
;                     *(LAS u32x4*)(QS + t * QST + dc) = qo; *(LAS u32x4*)(KS + t * QST + dc) = k; }
;                 ko.x = pk2(bflo(k.x) * wa, bfhi(k.x) * wa); ko.y = pk2(bflo(k.y) * wa, bfhi(k.y) * wa); ko.z = pk2(bflo(k.z) * wa, bfhi(k.z) * wa); ko.w = pk2(bflo(k.w) * wa, bfhi(k.w) * wa);
;                 *(LAS u32x4*)(K2 + t * QST + dc) = ko; }
.LBB0_532:
	s_waitcnt vmcnt(0) lgkmcnt(0)
	v_lshlrev_b32_e32 v101, 16, v97
	v_lshlrev_b32_e32 v100, 16, v96
	v_and_b32_e32 v97, 0xffff0000, v97
	v_and_b32_e32 v96, 0xffff0000, v96
	v_lshlrev_b32_e32 v103, 16, v99
	v_lshlrev_b32_e32 v102, 16, v98
	v_and_b32_e32 v99, 0xffff0000, v99
	v_and_b32_e32 v98, 0xffff0000, v98
	v_pk_mul_f32 v[96:97], v[96:97], s[64:65] op_sel_hi:[1,0]
	v_pk_mul_f32 v[98:99], v[98:99], s[64:65] op_sel_hi:[1,0]
	v_pk_mul_f32 v[100:101], v[100:101], s[64:65] op_sel_hi:[1,0]
	v_pk_mul_f32 v[102:103], v[102:103], s[64:65] op_sel_hi:[1,0]
	v_cvt_pk_bf16_f32 v96, v100, v96
	v_cvt_pk_bf16_f32 v97, v101, v97
	v_cvt_pk_bf16_f32 v98, v102, v98
	v_cvt_pk_bf16_f32 v99, v103, v99
	s_barrier
	ds_read_b32 v0, v148 offset:768
	ds_write_b128 v149, v[96:99]
	ds_write_b128 v149, v[92:95] offset:33792
	v_lshlrev_b32_e32 v97, 16, v93
	v_lshlrev_b32_e32 v96, 16, v92
	v_and_b32_e32 v93, 0xffff0000, v93
	v_and_b32_e32 v92, 0xffff0000, v92
	v_lshlrev_b32_e32 v99, 16, v95
	v_lshlrev_b32_e32 v98, 16, v94
	v_and_b32_e32 v95, 0xffff0000, v95
	v_and_b32_e32 v94, 0xffff0000, v94
	s_waitcnt lgkmcnt(2)
	v_pk_mul_f32 v[92:93], v[0:1], v[92:93] op_sel_hi:[0,1]
	v_pk_mul_f32 v[94:95], v[0:1], v[94:95] op_sel_hi:[0,1]
	v_pk_mul_f32 v[96:97], v[0:1], v[96:97] op_sel_hi:[0,1]
	v_pk_mul_f32 v[98:99], v[0:1], v[98:99] op_sel_hi:[0,1]
	v_cvt_pk_bf16_f32 v92, v96, v92
	v_cvt_pk_bf16_f32 v93, v97, v93
	v_cvt_pk_bf16_f32 v94, v98, v94
	v_cvt_pk_bf16_f32 v95, v99, v95
	ds_write_b128 v170, v[92:95]
	v_lshlrev_b32_e32 v93, 16, v89
	v_lshlrev_b32_e32 v92, 16, v88
	v_and_b32_e32 v89, 0xffff0000, v89
	v_and_b32_e32 v88, 0xffff0000, v88
	v_lshlrev_b32_e32 v95, 16, v91
	v_lshlrev_b32_e32 v94, 16, v90
	v_and_b32_e32 v91, 0xffff0000, v91
	v_and_b32_e32 v90, 0xffff0000, v90
	v_pk_mul_f32 v[88:89], v[88:89], s[64:65] op_sel_hi:[1,0]
	v_pk_mul_f32 v[90:91], v[90:91], s[64:65] op_sel_hi:[1,0]
	v_pk_mul_f32 v[92:93], v[92:93], s[64:65] op_sel_hi:[1,0]
	v_pk_mul_f32 v[94:95], v[94:95], s[64:65] op_sel_hi:[1,0]
	v_cvt_pk_bf16_f32 v88, v92, v88
	v_cvt_pk_bf16_f32 v89, v93, v89
	v_cvt_pk_bf16_f32 v90, v94, v90
	v_cvt_pk_bf16_f32 v91, v95, v91
	ds_read_b32 v0, v171 offset:768
	ds_write_b128 v172, v[88:91]
	ds_write_b128 v172, v[84:87] offset:33792
	v_lshlrev_b32_e32 v89, 16, v85
	v_lshlrev_b32_e32 v88, 16, v84
	v_and_b32_e32 v85, 0xffff0000, v85
	v_and_b32_e32 v84, 0xffff0000, v84
	v_lshlrev_b32_e32 v91, 16, v87
	v_lshlrev_b32_e32 v90, 16, v86
	v_and_b32_e32 v87, 0xffff0000, v87
	v_and_b32_e32 v86, 0xffff0000, v86
	s_waitcnt lgkmcnt(2)
	v_pk_mul_f32 v[84:85], v[0:1], v[84:85] op_sel_hi:[0,1]
	v_pk_mul_f32 v[86:87], v[0:1], v[86:87] op_sel_hi:[0,1]
	v_pk_mul_f32 v[88:89], v[0:1], v[88:89] op_sel_hi:[0,1]
	v_pk_mul_f32 v[90:91], v[0:1], v[90:91] op_sel_hi:[0,1]
	v_cvt_pk_bf16_f32 v84, v88, v84
	v_cvt_pk_bf16_f32 v85, v89, v85
	v_cvt_pk_bf16_f32 v86, v90, v86
	v_cvt_pk_bf16_f32 v87, v91, v87
	ds_write_b128 v173, v[84:87]
	v_lshlrev_b32_e32 v85, 16, v81
	v_lshlrev_b32_e32 v84, 16, v80
	v_and_b32_e32 v81, 0xffff0000, v81
	v_and_b32_e32 v80, 0xffff0000, v80
	v_lshlrev_b32_e32 v87, 16, v83
	v_lshlrev_b32_e32 v86, 16, v82
	v_and_b32_e32 v83, 0xffff0000, v83
	v_and_b32_e32 v82, 0xffff0000, v82
	v_pk_mul_f32 v[80:81], v[80:81], s[64:65] op_sel_hi:[1,0]
	v_pk_mul_f32 v[82:83], v[82:83], s[64:65] op_sel_hi:[1,0]
	v_pk_mul_f32 v[84:85], v[84:85], s[64:65] op_sel_hi:[1,0]
	v_pk_mul_f32 v[86:87], v[86:87], s[64:65] op_sel_hi:[1,0]
	v_cvt_pk_bf16_f32 v80, v84, v80
	v_cvt_pk_bf16_f32 v81, v85, v81
	v_cvt_pk_bf16_f32 v82, v86, v82
	v_cvt_pk_bf16_f32 v83, v87, v83
	ds_read_b32 v0, v174 offset:768
	ds_write_b128 v175, v[80:83]
	ds_write_b128 v175, v[76:79] offset:33792
	v_lshlrev_b32_e32 v81, 16, v77
	v_lshlrev_b32_e32 v80, 16, v76
	v_and_b32_e32 v77, 0xffff0000, v77
	v_and_b32_e32 v76, 0xffff0000, v76
	v_lshlrev_b32_e32 v83, 16, v79
	v_lshlrev_b32_e32 v82, 16, v78
	v_and_b32_e32 v79, 0xffff0000, v79
	v_and_b32_e32 v78, 0xffff0000, v78
	s_waitcnt lgkmcnt(2)
	v_pk_mul_f32 v[76:77], v[0:1], v[76:77] op_sel_hi:[0,1]
	v_pk_mul_f32 v[78:79], v[0:1], v[78:79] op_sel_hi:[0,1]
	v_pk_mul_f32 v[80:81], v[0:1], v[80:81] op_sel_hi:[0,1]
	v_pk_mul_f32 v[82:83], v[0:1], v[82:83] op_sel_hi:[0,1]
	v_cvt_pk_bf16_f32 v76, v80, v76
	v_cvt_pk_bf16_f32 v77, v81, v77
	v_cvt_pk_bf16_f32 v78, v82, v78
	v_cvt_pk_bf16_f32 v79, v83, v79
	ds_write_b128 v176, v[76:79]
	v_lshlrev_b32_e32 v77, 16, v73
	v_lshlrev_b32_e32 v76, 16, v72
	v_and_b32_e32 v73, 0xffff0000, v73
	v_and_b32_e32 v72, 0xffff0000, v72
	v_lshlrev_b32_e32 v79, 16, v75
	v_lshlrev_b32_e32 v78, 16, v74
	v_and_b32_e32 v75, 0xffff0000, v75
	v_and_b32_e32 v74, 0xffff0000, v74
	v_pk_mul_f32 v[72:73], v[72:73], s[64:65] op_sel_hi:[1,0]
	v_pk_mul_f32 v[74:75], v[74:75], s[64:65] op_sel_hi:[1,0]
	v_pk_mul_f32 v[76:77], v[76:77], s[64:65] op_sel_hi:[1,0]
	v_pk_mul_f32 v[78:79], v[78:79], s[64:65] op_sel_hi:[1,0]
	v_cvt_pk_bf16_f32 v72, v76, v72
	v_cvt_pk_bf16_f32 v73, v77, v73
	v_cvt_pk_bf16_f32 v74, v78, v74
	v_cvt_pk_bf16_f32 v75, v79, v75
	ds_read_b32 v0, v177 offset:768
	ds_write_b128 v178, v[72:75]
	ds_write_b128 v178, v[68:71] offset:33792
	v_lshlrev_b32_e32 v73, 16, v69
	v_lshlrev_b32_e32 v72, 16, v68
	v_and_b32_e32 v69, 0xffff0000, v69
	v_and_b32_e32 v68, 0xffff0000, v68
	v_lshlrev_b32_e32 v75, 16, v71
	v_lshlrev_b32_e32 v74, 16, v70
	v_and_b32_e32 v71, 0xffff0000, v71
	v_and_b32_e32 v70, 0xffff0000, v70
	s_waitcnt lgkmcnt(2)
	v_pk_mul_f32 v[68:69], v[0:1], v[68:69] op_sel_hi:[0,1]
	v_pk_mul_f32 v[70:71], v[0:1], v[70:71] op_sel_hi:[0,1]
	v_pk_mul_f32 v[72:73], v[0:1], v[72:73] op_sel_hi:[0,1]
	v_pk_mul_f32 v[74:75], v[0:1], v[74:75] op_sel_hi:[0,1]
	v_cvt_pk_bf16_f32 v68, v72, v68
	v_cvt_pk_bf16_f32 v69, v73, v69
	v_cvt_pk_bf16_f32 v70, v74, v70
	v_cvt_pk_bf16_f32 v71, v75, v71
	ds_write_b128 v179, v[68:71]
	s_waitcnt lgkmcnt(0)
	s_barrier
; #define LAS __attribute__((address_space(3)))
; __device__ __forceinline__ unsigned pk2(float lo, float hi) { return f2bf(lo) | (f2bf(hi) << 16); }
; #define MFMA16(a, b, c) __builtin_amdgcn_mfma_f32_16x16x32_bf16((a), (b), (c), 0, 0, 0)
; template <int KIND, int MODE>
; __device__ __forceinline__ void scan_unit(Frame& F, int layer, int h, int vhalf, int grp) {
;     ...
;         if (MODE == 1) {
;             const int stile = w >> 1;
; #pragma unroll
;             for (int tt = 0; tt < 2; ++tt) { const int ttile = 2 * (w & 1) + tt; f32x4 acc = (f32x4){0.f, 0.f, 0.f, 0.f};
; #pragma unroll
;                 for (int sl = 0; sl < NSL; ++sl) { const bf16x8 a = *(const LAS bf16x8*)(KS + (16 * stile + li) * QST + 32 * sl + 8 * g), bb = *(const LAS bf16x8*)(QS + (16 * ttile + li) * QST + 32 * sl + 8 * g); acc = MFMA16(a, bb, acc); }
;                 const int t = 16 * ttile + li; float p[4]; float rs = 0.f;
;                 float mt = 0.f; f32x4 cs = (f32x4){0.f, 0.f, 0.f, 0.f};
;                 if (KIND) { mt = X[64 + t]; cs = *(const LAS f32x4*)(X + 16 * stile + 4 * g); }
; #pragma unroll
;                 for (int r = 0; r < 4; ++r) { const int s = 16 * stile + 4 * g + r; float v = acc[r]; if (KIND) v *= __expf(fminf(cs[r] - mt, 0.f)); p[r] = (s <= t) ? v : 0.f; rs += p[r]; }
;                 u32x2 pw; pw.x = pk2(p[0], p[1]); pw.y = pk2(p[2], p[3]); *(LAS u32x2*)(PS + t * PST + 16 * stile + 4 * g) = pw;
;                 if (KIND) { rs += __shfl_xor(rs, 16); rs += __shfl_xor(rs, 32); if (g == 0) X[640 + stile * 64 + t] = rs; }
;             }
	ds_read_b128 v[68:71], v120 offset:33792
	ds_read_b128 v[72:75], v205
	ds_read_b128 v[76:79], v120 offset:33856
	ds_read_b128 v[80:83], v205 offset:64
	s_waitcnt lgkmcnt(2)
	v_mfma_f32_16x16x32_bf16 v[68:71], v[68:71], v[72:75], 0
	ds_read_b128 v[72:75], v120 offset:33920
	ds_read_b128 v[84:87], v205 offset:128
	s_waitcnt lgkmcnt(2)
	v_mfma_f32_16x16x32_bf16 v[68:71], v[76:79], v[80:83], v[68:71]
	ds_read_b128 v[76:79], v120 offset:33984
	ds_read_b128 v[80:83], v205 offset:192
	s_waitcnt lgkmcnt(2)
	v_mfma_f32_16x16x32_bf16 v[68:71], v[72:75], v[84:87], v[68:71]
	ds_read_b128 v[72:75], v120 offset:34048
	ds_read_b128 v[84:87], v205 offset:256
	s_waitcnt lgkmcnt(2)
	v_mfma_f32_16x16x32_bf16 v[68:71], v[76:79], v[80:83], v[68:71]
	ds_read_b128 v[76:79], v120 offset:34112
	ds_read_b128 v[80:83], v205 offset:320
	s_waitcnt lgkmcnt(2)
	v_mfma_f32_16x16x32_bf16 v[68:71], v[72:75], v[84:87], v[68:71]
	ds_read_b128 v[72:75], v120 offset:34176
	ds_read_b128 v[84:87], v205 offset:384
	s_waitcnt lgkmcnt(2)
	v_mfma_f32_16x16x32_bf16 v[68:71], v[76:79], v[80:83], v[68:71]
	ds_read_b128 v[76:79], v120 offset:34240
	ds_read_b128 v[80:83], v205 offset:448
	s_waitcnt lgkmcnt(2)
	v_mfma_f32_16x16x32_bf16 v[68:71], v[72:75], v[84:87], v[68:71]
	ds_read_b32 v0, v180 offset:256
	ds_read_b128 v[72:75], v121
	s_waitcnt lgkmcnt(0)
	v_sub_f32_e32 v73, v73, v0
	v_min_f32_e32 v73, 0, v73
	v_mul_f32_e32 v73, 0x3fb8aa3b, v73
	v_mfma_f32_16x16x32_bf16 v[68:71], v[76:79], v[80:83], v[68:71]
	v_sub_f32_e32 v72, v72, v0
	v_exp_f32_e32 v76, v73
	v_sub_f32_e32 v73, v74, v0
	v_min_f32_e32 v72, 0, v72
	v_min_f32_e32 v73, 0, v73
	v_mul_f32_e32 v72, 0x3fb8aa3b, v72
	v_sub_f32_e32 v0, v75, v0
	v_mul_f32_e32 v73, 0x3fb8aa3b, v73
	v_exp_f32_e32 v72, v72
	v_min_f32_e32 v0, 0, v0
	v_exp_f32_e32 v73, v73
	v_mul_f32_e32 v0, 0x3fb8aa3b, v0
	v_exp_f32_e32 v0, v0
	v_mul_f32_e32 v74, v69, v76
	v_mov_b32_e32 v69, v70
	v_pk_mul_f32 v[68:69], v[68:69], v[72:73]
	v_mul_f32_e32 v0, v71, v0
	v_cndmask_b32_e64 v68, v68, 0, s[24:25]
	v_add_f32_e32 v70, 0, v68
	v_cndmask_b32_e64 v71, 0, v74, s[28:29]
	v_cndmask_b32_e64 v69, v69, 0, s[26:27]
	v_add_f32_e32 v70, v71, v70
	v_cndmask_b32_e64 v0, v0, 0, s[30:31]
	v_add_f32_e32 v70, v69, v70
	v_add_f32_e32 v70, v0, v70
	v_cvt_pk_bf16_f32 v69, v69, v0
	ds_bpermute_b32 v72, v128, v70
	v_cvt_pk_bf16_f32 v73, v68, v71
	s_waitcnt lgkmcnt(0)
	v_add_f32_e32 v0, v70, v72
	ds_bpermute_b32 v68, v129, v0
	v_mov_b32_e32 v71, v69
	v_mov_b32_e32 v70, v73
	ds_write_b64 v206, v[70:71]
	s_and_saveexec_b64 s[0:1], s[12:13]
	s_cbranch_execz .LBB0_534
	s_waitcnt lgkmcnt(1)
	v_add_f32_e32 v0, v0, v68
	ds_write_b32 v181, v0 offset:2560
.LBB0_534:
	s_or_b64 exec, exec, s[0:1]
	s_waitcnt lgkmcnt(1)
	ds_read_b128 v[68:71], v120 offset:33792
	ds_read_b128 v[72:75], v205 offset:8448
	s_waitcnt lgkmcnt(0)
	v_mfma_f32_16x16x32_bf16 v[68:71], v[68:71], v[72:75], 0
	ds_read_b128 v[72:75], v120 offset:33856
	ds_read_b128 v[76:79], v205 offset:8512
	s_waitcnt lgkmcnt(0)
	v_mfma_f32_16x16x32_bf16 v[68:71], v[72:75], v[76:79], v[68:71]
	ds_read_b128 v[72:75], v120 offset:33920
	ds_read_b128 v[76:79], v205 offset:8576
	s_waitcnt lgkmcnt(0)
	v_mfma_f32_16x16x32_bf16 v[68:71], v[72:75], v[76:79], v[68:71]
	ds_read_b128 v[72:75], v120 offset:33984
	ds_read_b128 v[76:79], v205 offset:8640
	s_waitcnt lgkmcnt(0)
	v_mfma_f32_16x16x32_bf16 v[68:71], v[72:75], v[76:79], v[68:71]
	ds_read_b128 v[72:75], v120 offset:34048
	ds_read_b128 v[76:79], v205 offset:8704
	s_waitcnt lgkmcnt(0)
	v_mfma_f32_16x16x32_bf16 v[68:71], v[72:75], v[76:79], v[68:71]
	ds_read_b128 v[72:75], v120 offset:34112
	ds_read_b128 v[76:79], v205 offset:8768
	s_waitcnt lgkmcnt(0)
	v_mfma_f32_16x16x32_bf16 v[68:71], v[72:75], v[76:79], v[68:71]
	ds_read_b128 v[72:75], v120 offset:34176
	ds_read_b128 v[76:79], v205 offset:8832
	s_waitcnt lgkmcnt(0)
	v_mfma_f32_16x16x32_bf16 v[68:71], v[72:75], v[76:79], v[68:71]
	ds_read_b128 v[72:75], v120 offset:34240
	ds_read_b128 v[76:79], v205 offset:8896
	s_waitcnt lgkmcnt(0)
	v_mfma_f32_16x16x32_bf16 v[68:71], v[72:75], v[76:79], v[68:71]
	ds_read_b32 v0, v182 offset:256
	ds_read_b128 v[72:75], v121
	s_waitcnt lgkmcnt(0)
	v_sub_f32_e32 v72, v72, v0
	v_min_f32_e32 v72, 0, v72
	v_sub_f32_e32 v73, v73, v0
	v_mul_f32_e32 v72, 0x3fb8aa3b, v72
	v_min_f32_e32 v73, 0, v73
	v_exp_f32_e32 v72, v72
	v_mul_f32_e32 v73, 0x3fb8aa3b, v73
	v_exp_f32_e32 v73, v73
	v_mul_f32_e32 v68, v68, v72
	v_cndmask_b32_e64 v72, v68, 0, s[34:35]
	v_mul_f32_e32 v69, v69, v73
	v_add_f32_e32 v68, 0, v72
	v_cndmask_b32_e64 v73, 0, v69, s[36:37]
	v_add_f32_e32 v76, v73, v68
	v_sub_f32_e32 v68, v74, v0
	v_sub_f32_e32 v0, v75, v0
	v_min_f32_e32 v68, 0, v68
	v_min_f32_e32 v0, 0, v0
	v_mul_f32_e32 v68, 0x3fb8aa3b, v68
	v_mul_f32_e32 v0, 0x3fb8aa3b, v0
	v_exp_f32_e32 v68, v68
	v_exp_f32_e32 v69, v0
	s_nop 0
	v_pk_mul_f32 v[68:69], v[70:71], v[68:69]
	v_cndmask_b32_e64 v68, v68, 0, s[40:41]
	v_cvt_pk_bf16_f32 v72, v72, v73
	v_cndmask_b32_e64 v0, v69, 0, s[38:39]
	v_add_f32_e32 v69, v68, v76
	v_add_f32_e32 v69, v0, v69
	v_cvt_pk_bf16_f32 v73, v68, v0
	ds_bpermute_b32 v0, v128, v69
	ds_write_b64 v206, v[72:73] offset:2304
	s_waitcnt lgkmcnt(1)
	v_add_f32_e32 v0, v69, v0
	ds_bpermute_b32 v68, v129, v0
	s_and_saveexec_b64 s[0:1], s[12:13]
	s_cbranch_execz .LBB0_536
	s_waitcnt lgkmcnt(0)
	v_add_f32_e32 v0, v0, v68
	ds_write_b32 v181, v0 offset:2624
; #define LAS __attribute__((address_space(3)))
; #define MFMA16(a, b, c) __builtin_amdgcn_mfma_f32_16x16x32_bf16((a), (b), (c), 0, 0, 0)
; __device__ __forceinline__ s16x4 tr_read(const LAS unsigned short* p) { return __builtin_amdgcn_ds_read_tr16_b64_v4i16((LAS s16x4*)p); }
; __device__ __forceinline__ bf16x8 pack8(f32x4 a, f32x4 b) { u32x4 w; w.x = pk2(a[0], a[1]); w.y = pk2(a[2], a[3]); w.z = pk2(b[0], b[1]); w.w = pk2(b[2], b[3]); return __builtin_bit_cast(bf16x8, w); }
; template <int KIND, int MODE>
; __device__ __forceinline__ void scan_unit(Frame& F, int layer, int h, int vhalf, int grp) {
;     ...
;             if (KIND) { const int t = tid & 63, part = tid >> 6; float s = 0.f;
; #pragma unroll
;                 for (int i = 0; i < 4; ++i) { const u32x4 qv = *(const LAS u32x4*)(QS + t * QST + 32 * part + 8 * i); const LAS float* nn = X + 384 + 32 * part + 8 * i;
;                     s += bflo(qv.x) * nn[0] + bfhi(qv.x) * nn[1] + bflo(qv.y) * nn[2] + bfhi(qv.y) * nn[3] + bflo(qv.z) * nn[4] + bfhi(qv.z) * nn[5] + bflo(qv.w) * nn[6] + bfhi(qv.w) * nn[7]; }
;                 X[896 + part * 64 + t] = s; }
;         }
;         if (MODE == 1) __syncthreads();
;         {
;             bf16x8 vf[2];
; #pragma unroll
;             for (int ks = 0; ks < 2; ++ks) { const LAS unsigned short* vp = VS + (32 * ks + 8 * g + (li >> 2)) * VST + 16 * w + 4 * (li & 3); vf[ks] = cat8(tr_read(vp), tr_read(vp + 4 * VST)); }
;             bf16x8 sf[NSL];
; #pragma unroll
;             for (int i = 0; i < NSL; ++i) sf[i] = pack8(S[2 * i], S[2 * i + 1]);
;             if (MODE == 1)
; #pragma unroll
;             for (int tt = 0; tt < 4; ++tt) { const int t = 16 * tt + li; f32x4 oi = (f32x4){0.f, 0.f, 0.f, 0.f}, oe = (f32x4){0.f, 0.f, 0.f, 0.f};
; #pragma unroll
;                 for (int ks = 0; ks < 2; ++ks) { const bf16x8 pb = *(const LAS bf16x8*)(PS + t * PST + 32 * ks + 8 * g); oi = MFMA16(vf[ks], pb, oi); }
; #pragma unroll
;                 for (int i = 0; i < NSL; ++i) { const u32x2 q0 = *(const LAS u32x2*)(QS + t * QST + 32 * i + 4 * g), q1 = *(const LAS u32x2*)(QS + t * QST + 32 * i + 16 + 4 * g);
;                     const bf16x8 qb = __builtin_bit_cast(bf16x8, ((u32x4){q0.x, q0.y, q1.x, q1.y})); oe = MFMA16(sf[i], qb, oe); }
.LBB0_536:
	s_or_b64 exec, exec, s[0:1]
	s_waitcnt lgkmcnt(0)
	ds_read_b128 v[68:71], v130
	ds_read_b128 v[72:75], v130 offset:16
	ds_read_b128 v[76:79], v130 offset:32
	ds_read_b128 v[80:83], v130 offset:48
	ds_read_b128 v[84:87], v131
	ds_read_b128 v[88:91], v131 offset:16
	ds_read_b128 v[92:95], v131 offset:32
	ds_read_b128 v[96:99], v131 offset:48
	s_waitcnt lgkmcnt(7)
	v_and_b32_e32 v104, 0xffff0000, v68
	s_waitcnt lgkmcnt(6)
	v_and_b32_e32 v105, 0xffff0000, v72
	v_lshlrev_b32_e32 v101, 16, v72
	s_waitcnt lgkmcnt(1)
	v_mov_b32_e32 v103, v92
	v_mov_b32_e32 v92, v85
	v_lshlrev_b32_e32 v100, 16, v68
	v_mov_b32_e32 v102, v84
	v_pk_mul_f32 v[84:85], v[92:93], v[104:105]
	v_lshlrev_b32_e32 v93, 16, v73
	v_pk_fma_f32 v[84:85], v[102:103], v[100:101], v[84:85]
	v_lshlrev_b32_e32 v92, 16, v69
	v_mov_b32_e32 v100, v86
	v_mov_b32_e32 v101, v94
	v_pk_fma_f32 v[84:85], v[100:101], v[92:93], v[84:85]
	v_and_b32_e32 v73, 0xffff0000, v73
	v_and_b32_e32 v72, 0xffff0000, v69
	v_mov_b32_e32 v94, v87
	v_pk_fma_f32 v[68:69], v[94:95], v[72:73], v[84:85]
	v_lshlrev_b32_e32 v73, 16, v74
	v_lshlrev_b32_e32 v72, 16, v70
	v_mov_b32_e32 v84, v88
	s_waitcnt lgkmcnt(0)
	v_mov_b32_e32 v85, v96
	v_pk_fma_f32 v[68:69], v[84:85], v[72:73], v[68:69]
	v_and_b32_e32 v73, 0xffff0000, v74
	v_and_b32_e32 v72, 0xffff0000, v70
	v_mov_b32_e32 v96, v89
	v_pk_fma_f32 v[68:69], v[96:97], v[72:73], v[68:69]
	v_lshlrev_b32_e32 v73, 16, v75
	v_lshlrev_b32_e32 v72, 16, v71
	v_mov_b32_e32 v84, v90
	v_mov_b32_e32 v85, v98
	v_pk_fma_f32 v[68:69], v[84:85], v[72:73], v[68:69]
	v_and_b32_e32 v73, 0xffff0000, v75
	v_and_b32_e32 v72, 0xffff0000, v71
	v_mov_b32_e32 v98, v91
	v_pk_fma_f32 v[68:69], v[98:99], v[72:73], v[68:69]
	v_and_b32_e32 v97, 0xffff0000, v80
	v_add_f32_e32 v0, 0, v68
	v_add_f32_e32 v0, v0, v69
	ds_read_b128 v[68:71], v131 offset:80
	ds_read_b128 v[72:75], v131 offset:112
	ds_read_b128 v[84:87], v131 offset:64
	ds_read_b128 v[88:91], v131 offset:96
	v_and_b32_e32 v96, 0xffff0000, v76
	v_lshlrev_b32_e32 v93, 16, v80
	v_lshlrev_b32_e32 v92, 16, v76
	s_waitcnt lgkmcnt(1)
	v_mov_b32_e32 v94, v84
	s_waitcnt lgkmcnt(0)
	v_mov_b32_e32 v95, v88
	v_mov_b32_e32 v88, v85
	v_pk_mul_f32 v[84:85], v[88:89], v[96:97]
	v_lshlrev_b32_e32 v89, 16, v81
	v_pk_fma_f32 v[84:85], v[94:95], v[92:93], v[84:85]
	v_lshlrev_b32_e32 v88, 16, v77
	v_mov_b32_e32 v92, v86
	v_mov_b32_e32 v93, v90
	v_pk_fma_f32 v[84:85], v[92:93], v[88:89], v[84:85]
	v_and_b32_e32 v81, 0xffff0000, v81
	v_and_b32_e32 v80, 0xffff0000, v77
	v_mov_b32_e32 v90, v87
	v_pk_fma_f32 v[76:77], v[90:91], v[80:81], v[84:85]
	v_lshlrev_b32_e32 v81, 16, v82
	v_lshlrev_b32_e32 v80, 16, v78
	v_mov_b32_e32 v84, v68
	v_mov_b32_e32 v85, v72
	v_pk_fma_f32 v[76:77], v[84:85], v[80:81], v[76:77]
	v_and_b32_e32 v81, 0xffff0000, v82
	v_and_b32_e32 v80, 0xffff0000, v78
	v_mov_b32_e32 v72, v69
	v_pk_fma_f32 v[68:69], v[72:73], v[80:81], v[76:77]
	v_lshlrev_b32_e32 v73, 16, v83
	v_lshlrev_b32_e32 v72, 16, v79
	v_mov_b32_e32 v76, v70
	v_mov_b32_e32 v77, v74
	v_pk_fma_f32 v[68:69], v[76:77], v[72:73], v[68:69]
	v_and_b32_e32 v73, 0xffff0000, v83
	v_and_b32_e32 v72, 0xffff0000, v79
	v_mov_b32_e32 v74, v71
	v_pk_fma_f32 v[68:69], v[74:75], v[72:73], v[68:69]
	v_add_f32_e32 v0, v0, v68
	v_add_f32_e32 v0, v0, v69
	ds_write_b32 v132, v0 offset:3584
	v_cvt_pk_bf16_f32 v76, v24, v25
	v_cvt_pk_bf16_f32 v77, v26, v27
	v_cvt_pk_bf16_f32 v78, v4, v5
	v_cvt_pk_bf16_f32 v79, v6, v7
	v_cvt_pk_bf16_f32 v80, v60, v61
	v_cvt_pk_bf16_f32 v81, v62, v63
	v_cvt_pk_bf16_f32 v82, v8, v9
	v_cvt_pk_bf16_f32 v83, v10, v11
	v_cvt_pk_bf16_f32 v84, v12, v13
	v_cvt_pk_bf16_f32 v85, v14, v15
	v_cvt_pk_bf16_f32 v86, v16, v17
	v_cvt_pk_bf16_f32 v87, v18, v19
	v_cvt_pk_bf16_f32 v88, v20, v21
	v_cvt_pk_bf16_f32 v89, v22, v23
	v_cvt_pk_bf16_f32 v90, v28, v29
	v_cvt_pk_bf16_f32 v91, v30, v31
	v_cvt_pk_bf16_f32 v92, v32, v33
	v_cvt_pk_bf16_f32 v93, v34, v35
	v_cvt_pk_bf16_f32 v94, v36, v37
	v_cvt_pk_bf16_f32 v95, v38, v39
	s_waitcnt lgkmcnt(0)
	s_barrier
	ds_read_b64_tr_b16 v[72:73], v198
	ds_read_b64_tr_b16 v[74:75], v198 offset:1088
	ds_read_b64_tr_b16 v[68:69], v198 offset:8704
	ds_read_b64_tr_b16 v[70:71], v198 offset:9792
	ds_read_b128 v[108:111], v199
	ds_read_b128 v[112:115], v199 offset:64
	ds_read2_b64 v[208:211], v183 offset1:4
	v_cvt_pk_bf16_f32 v96, v40, v41
	v_cvt_pk_bf16_f32 v97, v42, v43
	ds_read2_b64 v[212:215], v183 offset0:8 offset1:12
	s_waitcnt lgkmcnt(1)
	v_mfma_f32_16x16x32_bf16 v[208:211], v[76:79], v[208:211], 0
	v_cvt_pk_bf16_f32 v98, v44, v45
	s_waitcnt lgkmcnt(0)
	v_mfma_f32_16x16x32_bf16 v[208:211], v[80:83], v[212:215], v[208:211]
	ds_read2_b64 v[212:215], v183 offset0:16 offset1:20
	v_cvt_pk_bf16_f32 v99, v46, v47
	v_cvt_pk_bf16_f32 v100, v48, v49
	s_waitcnt lgkmcnt(0)
	v_mfma_f32_16x16x32_bf16 v[208:211], v[84:87], v[212:215], v[208:211]
	ds_read2_b64 v[212:215], v183 offset0:24 offset1:28
	v_cvt_pk_bf16_f32 v101, v50, v51
	v_cvt_pk_bf16_f32 v102, v52, v53
	s_waitcnt lgkmcnt(0)
	v_mfma_f32_16x16x32_bf16 v[208:211], v[88:91], v[212:215], v[208:211]
	ds_read2_b64 v[212:215], v183 offset0:32 offset1:36
	v_cvt_pk_bf16_f32 v103, v54, v55
	s_waitcnt lgkmcnt(0)
	v_mfma_f32_16x16x32_bf16 v[208:211], v[92:95], v[212:215], v[208:211]
	ds_read2_b64 v[212:215], v183 offset0:40 offset1:44
	v_cvt_pk_bf16_f32 v104, v56, v57
	v_cvt_pk_bf16_f32 v105, v58, v59
	s_waitcnt lgkmcnt(0)
	v_mfma_f32_16x16x32_bf16 v[208:211], v[96:99], v[212:215], v[208:211]
	ds_read2_b64 v[212:215], v183 offset0:48 offset1:52
	v_cvt_pk_bf16_f32 v106, v64, v65
	v_cvt_pk_bf16_f32 v107, v66, v67
	s_waitcnt lgkmcnt(0)
; #define LAS __attribute__((address_space(3)))
; __device__ __forceinline__ unsigned pk2(float lo, float hi) { return f2bf(lo) | (f2bf(hi) << 16); }
; #define MFMA16(a, b, c) __builtin_amdgcn_mfma_f32_16x16x32_bf16((a), (b), (c), 0, 0, 0)
; template <int KIND, int MODE>
; __device__ __forceinline__ void scan_unit(Frame& F, int layer, int h, int vhalf, int grp) {
;     ...
;             for (int tt = 0; tt < 4; ++tt) { const int t = 16 * tt + li; f32x4 oi = (f32x4){0.f, 0.f, 0.f, 0.f}, oe = (f32x4){0.f, 0.f, 0.f, 0.f};
; #pragma unroll
;                 for (int ks = 0; ks < 2; ++ks) { const bf16x8 pb = *(const LAS bf16x8*)(PS + t * PST + 32 * ks + 8 * g); oi = MFMA16(vf[ks], pb, oi); }
; #pragma unroll
;                 for (int i = 0; i < NSL; ++i) { const u32x2 q0 = *(const LAS u32x2*)(QS + t * QST + 32 * i + 4 * g), q1 = *(const LAS u32x2*)(QS + t * QST + 32 * i + 16 + 4 * g);
;                     const bf16x8 qb = __builtin_bit_cast(bf16x8, ((u32x4){q0.x, q0.y, q1.x, q1.y})); oe = MFMA16(sf[i], qb, oe); }
;                 f32x4 o;
;                 if (KIND) { const float wi = X[128 + t]; float qn = wi * (((X[896 + t] + X[960 + t]) + (X[1024 + t] + X[1088 + t])) + ((X[1152 + t] + X[1216 + t]) + (X[1280 + t] + X[1344 + t])));
;                     qn += (X[640 + t] + X[704 + t]) + (X[768 + t] + X[832 + t]);
;                     const float inv = 1.0f / fmaxf(fabsf(qn), X[256 + t]); o = (oi + oe * wi) * inv; }
;                 else o = oi + oe;
;                 u32x2 ow; ow.x = pk2(o[0], o[1]); ow.y = pk2(o[2], o[3]); *(u32x2*)(yout + (size_t)(tb + t) * D) = ow;
;                 float sq = (o[0] * o[0] + o[1] * o[1]) + (o[2] * o[2] + o[3] * o[3]); sq += __shfl_xor(sq, 16); sq += __shfl_xor(sq, 32);
;                 if (g == 0) SSR[w * 64 + t] = sq;
;             }
	v_mfma_f32_16x16x32_bf16 v[208:211], v[100:103], v[212:215], v[208:211]
	ds_read2_b64 v[212:215], v183 offset0:56 offset1:60
	v_mfma_f32_16x16x32_bf16 v[108:111], v[72:75], v[108:111], 0
	s_waitcnt lgkmcnt(0)
	v_mfma_f32_16x16x32_bf16 v[208:211], v[104:107], v[212:215], v[208:211]
	v_mfma_f32_16x16x32_bf16 v[108:111], v[68:71], v[112:115], v[108:111]
	ds_read2st64_b32 v[112:113], v184 offset0:2 offset1:4
	ds_read2st64_b32 v[114:115], v184 offset0:14 offset1:15
	ds_read2st64_b32 v[166:167], v184 offset0:16 offset1:17
	ds_read2st64_b32 v[212:213], v184 offset0:18 offset1:19
	ds_read2st64_b32 v[214:215], v184 offset0:20 offset1:21
	ds_read2st64_b32 v[216:217], v184 offset0:10 offset1:11
	ds_read2st64_b32 v[218:219], v184 offset0:12 offset1:13
	s_waitcnt lgkmcnt(5)
	v_add_f32_e32 v114, v114, v115
	s_waitcnt lgkmcnt(4)
	v_add_f32_e32 v166, v166, v167
	s_waitcnt lgkmcnt(3)
	v_add_f32_e32 v212, v212, v213
	s_waitcnt lgkmcnt(2)
	v_add_f32_e32 v214, v214, v215
	s_waitcnt lgkmcnt(1)
	v_mov_b32_e32 v115, v216
	v_mov_b32_e32 v167, v217
	s_waitcnt lgkmcnt(0)
	v_mov_b32_e32 v213, v218
	v_mov_b32_e32 v215, v219
	v_pk_add_f32 v[114:115], v[114:115], v[166:167]
	v_pk_add_f32 v[166:167], v[212:213], v[214:215]
	v_max_f32_e32 v0, v113, v113
	v_pk_add_f32 v[114:115], v[114:115], v[166:167]
	s_nop 0
	v_fmac_f32_e32 v115, v112, v114
	v_max_f32_e64 v0, |v115|, v0
	v_div_scale_f32 v113, s[0:1], v0, v0, 1.0
	v_rcp_f32_e32 v114, v113
	s_nop 0
	v_fma_f32 v115, -v113, v114, 1.0
	v_fmac_f32_e32 v114, v115, v114
	v_div_scale_f32 v115, vcc, 1.0, v0, 1.0
	v_mul_f32_e32 v166, v115, v114
	v_fma_f32 v167, -v113, v166, v115
	v_fmac_f32_e32 v166, v167, v114
	v_fma_f32 v113, -v113, v166, v115
	v_div_fmas_f32 v113, v113, v114, v166
	v_div_fixup_f32 v0, v113, v0, 1.0
	v_pk_fma_f32 v[110:111], v[210:211], v[112:113], v[110:111] op_sel_hi:[1,0,1]
	v_pk_fma_f32 v[108:109], v[208:209], v[112:113], v[108:109] op_sel_hi:[1,0,1]
	v_pk_mul_f32 v[110:111], v[110:111], v[0:1] op_sel_hi:[1,0]
	v_pk_mul_f32 v[108:109], v[108:109], v[0:1] op_sel_hi:[1,0]
	v_cvt_pk_bf16_f32 v113, v110, v111
	v_mul_f32_e32 v0, v109, v109
	v_cvt_pk_bf16_f32 v112, v108, v109
	v_fmac_f32_e32 v0, v108, v108
	v_mul_f32_e32 v108, v111, v111
	v_fmac_f32_e32 v108, v110, v110
	v_add_f32_e32 v0, v0, v108
	ds_bpermute_b32 v108, v128, v0
	s_waitcnt lgkmcnt(0)
	v_add_f32_e32 v0, v0, v108
	ds_bpermute_b32 v108, v129, v0
	v_or_b32_e32 v114, s44, v117
	v_ashrrev_i32_e32 v115, 31, v114
	v_lshlrev_b64 v[114:115], 11, v[114:115]
	v_lshl_add_u64 v[114:115], v[2:3], 0, v[114:115]
	flat_store_dwordx2 v[114:115], v[112:113]
	s_and_saveexec_b64 s[0:1], s[12:13]
	s_cbranch_execz .LBB0_538
	s_waitcnt lgkmcnt(0)
	v_add_f32_e32 v0, v0, v108
	ds_write_b32 v185, v0
.LBB0_538:
	s_or_b64 exec, exec, s[0:1]
	s_waitcnt lgkmcnt(0)
	ds_read_b128 v[108:111], v200
	ds_read_b128 v[112:115], v200 offset:64
	ds_read2_b64 v[208:211], v187 offset1:4
	ds_read2_b64 v[212:215], v187 offset0:8 offset1:12
	s_waitcnt lgkmcnt(0)
	v_mfma_f32_16x16x32_bf16 v[108:111], v[72:75], v[108:111], 0
	v_mfma_f32_16x16x32_bf16 v[208:211], v[76:79], v[208:211], 0
	v_mfma_f32_16x16x32_bf16 v[208:211], v[80:83], v[212:215], v[208:211]
	ds_read2_b64 v[212:215], v187 offset0:16 offset1:20
	s_waitcnt lgkmcnt(0)
	v_mfma_f32_16x16x32_bf16 v[208:211], v[84:87], v[212:215], v[208:211]
	ds_read2_b64 v[212:215], v187 offset0:24 offset1:28
	s_waitcnt lgkmcnt(0)
	v_mfma_f32_16x16x32_bf16 v[208:211], v[88:91], v[212:215], v[208:211]
	ds_read2_b64 v[212:215], v187 offset0:32 offset1:36
	s_waitcnt lgkmcnt(0)
	v_mfma_f32_16x16x32_bf16 v[208:211], v[92:95], v[212:215], v[208:211]
	ds_read2_b64 v[212:215], v187 offset0:40 offset1:44
	s_waitcnt lgkmcnt(0)
	v_mfma_f32_16x16x32_bf16 v[208:211], v[96:99], v[212:215], v[208:211]
	ds_read2_b64 v[212:215], v187 offset0:48 offset1:52
	s_waitcnt lgkmcnt(0)
	v_mfma_f32_16x16x32_bf16 v[208:211], v[100:103], v[212:215], v[208:211]
	ds_read2_b64 v[212:215], v187 offset0:56 offset1:60
	s_waitcnt lgkmcnt(0)
	v_mfma_f32_16x16x32_bf16 v[208:211], v[104:107], v[212:215], v[208:211]
	v_mfma_f32_16x16x32_bf16 v[108:111], v[68:71], v[112:115], v[108:111]
	ds_read2st64_b32 v[112:113], v188 offset0:2 offset1:4
	ds_read2st64_b32 v[114:115], v188 offset0:14 offset1:15
	ds_read2st64_b32 v[166:167], v188 offset0:16 offset1:17
	ds_read2st64_b32 v[212:213], v188 offset0:18 offset1:19
	ds_read2st64_b32 v[214:215], v188 offset0:20 offset1:21
	ds_read2st64_b32 v[216:217], v188 offset0:10 offset1:11
	ds_read2st64_b32 v[218:219], v188 offset0:12 offset1:13
	s_waitcnt lgkmcnt(0)
	v_add_f32_e32 v114, v114, v115
	v_add_f32_e32 v166, v166, v167
	v_add_f32_e32 v212, v212, v213
	v_add_f32_e32 v214, v214, v215
	v_mov_b32_e32 v115, v216
	v_mov_b32_e32 v167, v217
	v_mov_b32_e32 v213, v218
	v_mov_b32_e32 v215, v219
	v_pk_add_f32 v[114:115], v[114:115], v[166:167]
	v_pk_add_f32 v[166:167], v[212:213], v[214:215]
	v_max_f32_e32 v0, v113, v113
	v_pk_add_f32 v[114:115], v[114:115], v[166:167]
	s_nop 0
	v_fmac_f32_e32 v115, v112, v114
	v_max_f32_e64 v0, |v115|, v0
	v_div_scale_f32 v113, s[0:1], v0, v0, 1.0
	v_rcp_f32_e32 v114, v113
	s_nop 0
	v_fma_f32 v115, -v113, v114, 1.0
	v_fmac_f32_e32 v114, v115, v114
	v_div_scale_f32 v115, vcc, 1.0, v0, 1.0
	v_mul_f32_e32 v166, v115, v114
	v_fma_f32 v167, -v113, v166, v115
	v_fmac_f32_e32 v166, v167, v114
	v_fma_f32 v113, -v113, v166, v115
	v_div_fmas_f32 v113, v113, v114, v166
	v_div_fixup_f32 v0, v113, v0, 1.0
	v_pk_fma_f32 v[110:111], v[210:211], v[112:113], v[110:111] op_sel_hi:[1,0,1]
	v_pk_fma_f32 v[108:109], v[208:209], v[112:113], v[108:109] op_sel_hi:[1,0,1]
	v_pk_mul_f32 v[110:111], v[110:111], v[0:1] op_sel_hi:[1,0]
	v_pk_mul_f32 v[108:109], v[108:109], v[0:1] op_sel_hi:[1,0]
	v_cvt_pk_bf16_f32 v113, v110, v111
	v_mul_f32_e32 v0, v109, v109
	v_cvt_pk_bf16_f32 v112, v108, v109
	v_fmac_f32_e32 v0, v108, v108
	v_mul_f32_e32 v108, v111, v111
	v_fmac_f32_e32 v108, v110, v110
	v_add_f32_e32 v0, v0, v108
	ds_bpermute_b32 v108, v128, v0
	s_waitcnt lgkmcnt(0)
	v_add_f32_e32 v0, v0, v108
	ds_bpermute_b32 v108, v129, v0
	v_or_b32_e32 v114, s44, v186
	v_ashrrev_i32_e32 v115, 31, v114
	v_lshlrev_b64 v[114:115], 11, v[114:115]
	v_lshl_add_u64 v[114:115], v[2:3], 0, v[114:115]
	flat_store_dwordx2 v[114:115], v[112:113]
	s_and_saveexec_b64 s[0:1], s[12:13]
	s_cbranch_execz .LBB0_540
	s_waitcnt lgkmcnt(0)
	v_add_f32_e32 v0, v0, v108
	ds_write_b32 v185, v0 offset:64
; #define LAS __attribute__((address_space(3)))
; __device__ __forceinline__ unsigned pk2(float lo, float hi) { return f2bf(lo) | (f2bf(hi) << 16); }
; #define MFMA16(a, b, c) __builtin_amdgcn_mfma_f32_16x16x32_bf16((a), (b), (c), 0, 0, 0)
; template <int KIND, int MODE>
; __device__ __forceinline__ void scan_unit(Frame& F, int layer, int h, int vhalf, int grp) {
;     ...
;             for (int tt = 0; tt < 4; ++tt) { const int t = 16 * tt + li; f32x4 oi = (f32x4){0.f, 0.f, 0.f, 0.f}, oe = (f32x4){0.f, 0.f, 0.f, 0.f};
; #pragma unroll
;                 for (int ks = 0; ks < 2; ++ks) { const bf16x8 pb = *(const LAS bf16x8*)(PS + t * PST + 32 * ks + 8 * g); oi = MFMA16(vf[ks], pb, oi); }
; #pragma unroll
;                 for (int i = 0; i < NSL; ++i) { const u32x2 q0 = *(const LAS u32x2*)(QS + t * QST + 32 * i + 4 * g), q1 = *(const LAS u32x2*)(QS + t * QST + 32 * i + 16 + 4 * g);
;                     const bf16x8 qb = __builtin_bit_cast(bf16x8, ((u32x4){q0.x, q0.y, q1.x, q1.y})); oe = MFMA16(sf[i], qb, oe); }
;                 f32x4 o;
;                 if (KIND) { const float wi = X[128 + t]; float qn = wi * (((X[896 + t] + X[960 + t]) + (X[1024 + t] + X[1088 + t])) + ((X[1152 + t] + X[1216 + t]) + (X[1280 + t] + X[1344 + t])));
;                     qn += (X[640 + t] + X[704 + t]) + (X[768 + t] + X[832 + t]);
;                     const float inv = 1.0f / fmaxf(fabsf(qn), X[256 + t]); o = (oi + oe * wi) * inv; }
;                 else o = oi + oe;
;                 u32x2 ow; ow.x = pk2(o[0], o[1]); ow.y = pk2(o[2], o[3]); *(u32x2*)(yout + (size_t)(tb + t) * D) = ow;
;                 float sq = (o[0] * o[0] + o[1] * o[1]) + (o[2] * o[2] + o[3] * o[3]); sq += __shfl_xor(sq, 16); sq += __shfl_xor(sq, 32);
;                 if (g == 0) SSR[w * 64 + t] = sq;
;             }
.LBB0_540:
	s_or_b64 exec, exec, s[0:1]
	s_waitcnt lgkmcnt(0)
	ds_read_b128 v[108:111], v201
	ds_read_b128 v[112:115], v201 offset:64
	ds_read2_b64 v[208:211], v190 offset1:4
	ds_read2_b64 v[212:215], v190 offset0:8 offset1:12
	s_waitcnt lgkmcnt(0)
	v_mfma_f32_16x16x32_bf16 v[108:111], v[72:75], v[108:111], 0
	v_mfma_f32_16x16x32_bf16 v[208:211], v[76:79], v[208:211], 0
	v_mfma_f32_16x16x32_bf16 v[208:211], v[80:83], v[212:215], v[208:211]
	ds_read2_b64 v[212:215], v190 offset0:16 offset1:20
	s_waitcnt lgkmcnt(0)
	v_mfma_f32_16x16x32_bf16 v[208:211], v[84:87], v[212:215], v[208:211]
	ds_read2_b64 v[212:215], v190 offset0:24 offset1:28
	s_waitcnt lgkmcnt(0)
	v_mfma_f32_16x16x32_bf16 v[208:211], v[88:91], v[212:215], v[208:211]
	ds_read2_b64 v[212:215], v190 offset0:32 offset1:36
	s_waitcnt lgkmcnt(0)
	v_mfma_f32_16x16x32_bf16 v[208:211], v[92:95], v[212:215], v[208:211]
	ds_read2_b64 v[212:215], v190 offset0:40 offset1:44
	s_waitcnt lgkmcnt(0)
	v_mfma_f32_16x16x32_bf16 v[208:211], v[96:99], v[212:215], v[208:211]
	ds_read2_b64 v[212:215], v190 offset0:48 offset1:52
	s_waitcnt lgkmcnt(0)
	v_mfma_f32_16x16x32_bf16 v[208:211], v[100:103], v[212:215], v[208:211]
	ds_read2_b64 v[212:215], v190 offset0:56 offset1:60
	s_waitcnt lgkmcnt(0)
	v_mfma_f32_16x16x32_bf16 v[208:211], v[104:107], v[212:215], v[208:211]
	v_mfma_f32_16x16x32_bf16 v[108:111], v[68:71], v[112:115], v[108:111]
	ds_read2st64_b32 v[112:113], v191 offset0:2 offset1:4
	ds_read2st64_b32 v[114:115], v191 offset0:14 offset1:15
	ds_read2st64_b32 v[166:167], v191 offset0:16 offset1:17
	ds_read2st64_b32 v[212:213], v191 offset0:18 offset1:19
	ds_read2st64_b32 v[214:215], v191 offset0:20 offset1:21
	ds_read2st64_b32 v[216:217], v191 offset0:10 offset1:11
	ds_read2st64_b32 v[218:219], v191 offset0:12 offset1:13
	s_waitcnt lgkmcnt(0)
	v_add_f32_e32 v114, v114, v115
	v_add_f32_e32 v166, v166, v167
	v_add_f32_e32 v212, v212, v213
	v_add_f32_e32 v214, v214, v215
	v_mov_b32_e32 v115, v216
	v_mov_b32_e32 v167, v217
	v_mov_b32_e32 v213, v218
	v_mov_b32_e32 v215, v219
	v_pk_add_f32 v[114:115], v[114:115], v[166:167]
	v_pk_add_f32 v[166:167], v[212:213], v[214:215]
	v_max_f32_e32 v0, v113, v113
	v_pk_add_f32 v[114:115], v[114:115], v[166:167]
	s_nop 0
	v_fmac_f32_e32 v115, v112, v114
	v_max_f32_e64 v0, |v115|, v0
	v_div_scale_f32 v113, s[0:1], v0, v0, 1.0
	v_rcp_f32_e32 v114, v113
	s_nop 0
	v_fma_f32 v115, -v113, v114, 1.0
	v_fmac_f32_e32 v114, v115, v114
	v_div_scale_f32 v115, vcc, 1.0, v0, 1.0
	v_mul_f32_e32 v166, v115, v114
	v_fma_f32 v167, -v113, v166, v115
	v_fmac_f32_e32 v166, v167, v114
	v_fma_f32 v113, -v113, v166, v115
	v_div_fmas_f32 v113, v113, v114, v166
	v_div_fixup_f32 v0, v113, v0, 1.0
	v_pk_fma_f32 v[110:111], v[210:211], v[112:113], v[110:111] op_sel_hi:[1,0,1]
	v_pk_fma_f32 v[108:109], v[208:209], v[112:113], v[108:109] op_sel_hi:[1,0,1]
	v_pk_mul_f32 v[110:111], v[110:111], v[0:1] op_sel_hi:[1,0]
	v_pk_mul_f32 v[108:109], v[108:109], v[0:1] op_sel_hi:[1,0]
	v_cvt_pk_bf16_f32 v113, v110, v111
	v_mul_f32_e32 v0, v109, v109
	v_cvt_pk_bf16_f32 v112, v108, v109
	v_fmac_f32_e32 v0, v108, v108
	v_mul_f32_e32 v108, v111, v111
	v_fmac_f32_e32 v108, v110, v110
	v_add_f32_e32 v0, v0, v108
	ds_bpermute_b32 v108, v128, v0
	s_waitcnt lgkmcnt(0)
	v_add_f32_e32 v0, v0, v108
	ds_bpermute_b32 v108, v129, v0
	v_or_b32_e32 v114, s44, v189
	v_ashrrev_i32_e32 v115, 31, v114
	v_lshlrev_b64 v[114:115], 11, v[114:115]
	v_lshl_add_u64 v[114:115], v[2:3], 0, v[114:115]
	flat_store_dwordx2 v[114:115], v[112:113]
	s_and_saveexec_b64 s[0:1], s[12:13]
	s_cbranch_execz .LBB0_542
	s_waitcnt lgkmcnt(0)
	v_add_f32_e32 v0, v0, v108
	ds_write_b32 v185, v0 offset:128
; #define LAS __attribute__((address_space(3)))
; __device__ __forceinline__ unsigned pk2(float lo, float hi) { return f2bf(lo) | (f2bf(hi) << 16); }
; #define MFMA16(a, b, c) __builtin_amdgcn_mfma_f32_16x16x32_bf16((a), (b), (c), 0, 0, 0)
; template <int KIND, int MODE>
; __device__ __forceinline__ void scan_unit(Frame& F, int layer, int h, int vhalf, int grp) {
;     ...
;             for (int tt = 0; tt < 4; ++tt) { const int t = 16 * tt + li; f32x4 oi = (f32x4){0.f, 0.f, 0.f, 0.f}, oe = (f32x4){0.f, 0.f, 0.f, 0.f};
; #pragma unroll
;                 for (int ks = 0; ks < 2; ++ks) { const bf16x8 pb = *(const LAS bf16x8*)(PS + t * PST + 32 * ks + 8 * g); oi = MFMA16(vf[ks], pb, oi); }
; #pragma unroll
;                 for (int i = 0; i < NSL; ++i) { const u32x2 q0 = *(const LAS u32x2*)(QS + t * QST + 32 * i + 4 * g), q1 = *(const LAS u32x2*)(QS + t * QST + 32 * i + 16 + 4 * g);
;                     const bf16x8 qb = __builtin_bit_cast(bf16x8, ((u32x4){q0.x, q0.y, q1.x, q1.y})); oe = MFMA16(sf[i], qb, oe); }
;                 f32x4 o;
;                 if (KIND) { const float wi = X[128 + t]; float qn = wi * (((X[896 + t] + X[960 + t]) + (X[1024 + t] + X[1088 + t])) + ((X[1152 + t] + X[1216 + t]) + (X[1280 + t] + X[1344 + t])));
;                     qn += (X[640 + t] + X[704 + t]) + (X[768 + t] + X[832 + t]);
;                     const float inv = 1.0f / fmaxf(fabsf(qn), X[256 + t]); o = (oi + oe * wi) * inv; }
;                 else o = oi + oe;
;                 u32x2 ow; ow.x = pk2(o[0], o[1]); ow.y = pk2(o[2], o[3]); *(u32x2*)(yout + (size_t)(tb + t) * D) = ow;
;                 float sq = (o[0] * o[0] + o[1] * o[1]) + (o[2] * o[2] + o[3] * o[3]); sq += __shfl_xor(sq, 16); sq += __shfl_xor(sq, 32);
;                 if (g == 0) SSR[w * 64 + t] = sq;
;             }
.LBB0_542:
	s_or_b64 exec, exec, s[0:1]
	s_waitcnt lgkmcnt(0)
	ds_read_b128 v[108:111], v202
	ds_read_b128 v[112:115], v202 offset:64
	ds_read2_b64 v[208:211], v193 offset1:4
	s_waitcnt lgkmcnt(0)
	v_mfma_f32_16x16x32_bf16 v[76:79], v[76:79], v[208:211], 0
	ds_read2_b64 v[208:211], v193 offset0:8 offset1:12
	s_waitcnt lgkmcnt(0)
	v_mfma_f32_16x16x32_bf16 v[76:79], v[80:83], v[208:211], v[76:79]
	ds_read2_b64 v[80:83], v193 offset0:16 offset1:20
	s_waitcnt lgkmcnt(0)
	v_mfma_f32_16x16x32_bf16 v[76:79], v[84:87], v[80:83], v[76:79]
	ds_read2_b64 v[80:83], v193 offset0:24 offset1:28
	s_waitcnt lgkmcnt(0)
	v_mfma_f32_16x16x32_bf16 v[76:79], v[88:91], v[80:83], v[76:79]
	ds_read2_b64 v[80:83], v193 offset0:32 offset1:36
	s_waitcnt lgkmcnt(0)
	v_mfma_f32_16x16x32_bf16 v[76:79], v[92:95], v[80:83], v[76:79]
	ds_read2_b64 v[80:83], v193 offset0:40 offset1:44
	s_waitcnt lgkmcnt(0)
	v_mfma_f32_16x16x32_bf16 v[76:79], v[96:99], v[80:83], v[76:79]
	ds_read2_b64 v[80:83], v193 offset0:48 offset1:52
	s_waitcnt lgkmcnt(0)
	v_mfma_f32_16x16x32_bf16 v[76:79], v[100:103], v[80:83], v[76:79]
	ds_read2_b64 v[80:83], v193 offset0:56 offset1:60
	ds_read2st64_b32 v[84:85], v194 offset0:2 offset1:4
	ds_read2st64_b32 v[86:87], v194 offset0:14 offset1:15
	ds_read2st64_b32 v[88:89], v194 offset0:16 offset1:17
	ds_read2st64_b32 v[90:91], v194 offset0:18 offset1:19
	ds_read2st64_b32 v[92:93], v194 offset0:20 offset1:21
	ds_read2st64_b32 v[94:95], v194 offset0:10 offset1:11
	ds_read2st64_b32 v[96:97], v194 offset0:12 offset1:13
	s_waitcnt lgkmcnt(0)
	v_add_f32_e32 v86, v86, v87
	v_add_f32_e32 v88, v88, v89
	v_add_f32_e32 v90, v90, v91
	v_add_f32_e32 v92, v92, v93
	v_mov_b32_e32 v87, v94
	v_mov_b32_e32 v89, v95
	v_mov_b32_e32 v91, v96
	v_mov_b32_e32 v93, v97
	v_pk_add_f32 v[86:87], v[86:87], v[88:89]
	v_pk_add_f32 v[88:89], v[90:91], v[92:93]
	v_max_f32_e32 v0, v85, v85
	v_pk_add_f32 v[86:87], v[86:87], v[88:89]
	v_mfma_f32_16x16x32_bf16 v[76:79], v[104:107], v[80:83], v[76:79]
	v_fmac_f32_e32 v87, v84, v86
	v_max_f32_e64 v0, |v87|, v0
	v_div_scale_f32 v85, s[0:1], v0, v0, 1.0
	v_rcp_f32_e32 v86, v85
	v_mfma_f32_16x16x32_bf16 v[80:83], v[72:75], v[108:111], 0
	v_fma_f32 v87, -v85, v86, 1.0
	v_fmac_f32_e32 v86, v87, v86
	v_div_scale_f32 v87, vcc, 1.0, v0, 1.0
	v_mul_f32_e32 v88, v87, v86
	v_mfma_f32_16x16x32_bf16 v[80:83], v[68:71], v[112:115], v[80:83]
	v_fma_f32 v89, -v85, v88, v87
	v_fmac_f32_e32 v88, v89, v86
	v_fma_f32 v85, -v85, v88, v87
	v_div_fmas_f32 v85, v85, v86, v88
	v_div_fixup_f32 v0, v85, v0, 1.0
	s_nop 2
	v_pk_fma_f32 v[78:79], v[78:79], v[84:85], v[82:83] op_sel_hi:[1,0,1]
	v_pk_fma_f32 v[76:77], v[76:77], v[84:85], v[80:81] op_sel_hi:[1,0,1]
	v_pk_mul_f32 v[78:79], v[78:79], v[0:1] op_sel_hi:[1,0]
	v_pk_mul_f32 v[76:77], v[76:77], v[0:1] op_sel_hi:[1,0]
	v_cvt_pk_bf16_f32 v81, v78, v79
	v_mul_f32_e32 v0, v77, v77
	v_cvt_pk_bf16_f32 v80, v76, v77
	v_fmac_f32_e32 v0, v76, v76
	v_mul_f32_e32 v76, v79, v79
	v_fmac_f32_e32 v76, v78, v78
	v_add_f32_e32 v0, v0, v76
	ds_bpermute_b32 v76, v128, v0
	s_waitcnt lgkmcnt(0)
	v_add_f32_e32 v0, v0, v76
	ds_bpermute_b32 v76, v129, v0
	v_or_b32_e32 v82, s44, v192
	v_ashrrev_i32_e32 v83, 31, v82
	v_lshlrev_b64 v[82:83], 11, v[82:83]
	v_lshl_add_u64 v[82:83], v[2:3], 0, v[82:83]
	flat_store_dwordx2 v[82:83], v[80:81]
	s_and_saveexec_b64 s[0:1], s[12:13]
	s_cbranch_execz .LBB0_544
	s_waitcnt lgkmcnt(0)
	v_add_f32_e32 v0, v0, v76
	ds_write_b32 v185, v0 offset:192

; #define LAS __attribute__((address_space(3)))
; template <int KIND, int MODE>
; __device__ __forceinline__ void scan_unit(Frame& F, int layer, int h, int vhalf, int grp) {
;     ...
;         if (MODE == 1) {
;             const int stile = w >> 1;
; #pragma unroll
;             for (int tt = 0; tt < 2; ++tt) { const int ttile = 2 * (w & 1) + tt; f32x4 acc = (f32x4){0.f, 0.f, 0.f, 0.f};
; #pragma unroll
;                 for (int sl = 0; sl < NSL; ++sl) { const bf16x8 a = *(const LAS bf16x8*)(KS + (16 * stile + li) * QST + 32 * sl + 8 * g), bb = *(const LAS bf16x8*)(QS + (16 * ttile + li) * QST + 32 * sl + 8 * g); acc = MFMA16(a, bb, acc); }
;                 const int t = 16 * ttile + li; float p[4]; float rs = 0.f;
;                 float mt = 0.f; f32x4 cs = (f32x4){0.f, 0.f, 0.f, 0.f};
;                 if (KIND) { mt = X[64 + t]; cs = *(const LAS f32x4*)(X + 16 * stile + 4 * g); }
; #pragma unroll
;                 for (int r = 0; r < 4; ++r) { const int s = 16 * stile + 4 * g + r; float v = acc[r]; if (KIND) v *= __expf(fminf(cs[r] - mt, 0.f)); p[r] = (s <= t) ? v : 0.f; rs += p[r]; }
;                 u32x2 pw; pw.x = pk2(p[0], p[1]); pw.y = pk2(p[2], p[3]); *(LAS u32x2*)(PS + t * PST + 16 * stile + 4 * g) = pw;
;                 if (KIND) { rs += __shfl_xor(rs, 16); rs += __shfl_xor(rs, 32); if (g == 0) X[640 + stile * 64 + t] = rs; }
;             }
;             if (KIND) { const int t = tid & 63, part = tid >> 6; float s = 0.f;
; #pragma unroll
;                 for (int i = 0; i < 4; ++i) { const u32x4 qv = *(const LAS u32x4*)(QS + t * QST + 32 * part + 8 * i); const LAS float* nn = X + 384 + 32 * part + 8 * i;
;                     s += bflo(qv.x) * nn[0] + bfhi(qv.x) * nn[1] + bflo(qv.y) * nn[2] + bfhi(qv.y) * nn[3] + bflo(qv.z) * nn[4] + bfhi(qv.z) * nn[5] + bflo(qv.w) * nn[6] + bfhi(qv.w) * nn[7]; }
;                 X[896 + part * 64 + t] = s; }
;         }
;         if (MODE == 1) __syncthreads();
;         {
;             bf16x8 vf[2];
; #pragma unroll
;             for (int ks = 0; ks < 2; ++ks) { const LAS unsigned short* vp = VS + (32 * ks + 8 * g + (li >> 2)) * VST + 16 * w + 4 * (li & 3); vf[ks] = cat8(tr_read(vp), tr_read(vp + 4 * VST)); }
;             bf16x8 sf[NSL];
; #pragma unroll
;             for (int i = 0; i < NSL; ++i) sf[i] = pack8(S[2 * i], S[2 * i + 1]);
;             if (MODE == 1)
; #pragma unroll
.LBB0_562:
	s_waitcnt lgkmcnt(0)
	s_barrier
	ds_read_b128 v[58:61], v88 offset:33792
	ds_read_b128 v[62:65], v88 offset:33856
	ds_read_b128 v[66:69], v172
	ds_read_b128 v[70:73], v172 offset:64
	s_waitcnt lgkmcnt(0)
	v_mfma_f32_16x16x32_bf16 v[58:61], v[58:61], v[66:69], 0
	ds_read_b128 v[66:69], v88 offset:33920
	ds_read_b128 v[74:77], v88 offset:33984
	s_waitcnt lgkmcnt(2)
	v_mfma_f32_16x16x32_bf16 v[58:61], v[62:65], v[70:73], v[58:61]
	ds_read_b128 v[62:65], v172 offset:128
	ds_read_b128 v[70:73], v172 offset:192
	s_waitcnt lgkmcnt(0)
	v_mfma_f32_16x16x32_bf16 v[58:61], v[66:69], v[62:65], v[58:61]
	s_waitcnt lgkmcnt(0)
	v_mfma_f32_16x16x32_bf16 v[58:61], v[74:77], v[70:73], v[58:61]
	v_and_b32_e32 v93, 64, v225
	v_add_u32_e32 v93, 64, v93
	s_nop 2
	s_nop 2
	v_cndmask_b32_e64 v58, v58, 0, s[22:23]
	v_cndmask_b32_e64 v60, v60, 0, s[26:27]
	v_cndmask_b32_e64 v59, 0, v59, s[24:25]
	v_cndmask_b32_e64 v61, v61, 0, s[28:29]
	v_cvt_pk_bf16_f32 v58, v58, v59
	v_cvt_pk_bf16_f32 v59, v60, v61
	ds_write_b64 v173, v[58:59]
	ds_read_b128 v[58:61], v88 offset:33792
	ds_read_b128 v[62:65], v88 offset:33856
	ds_read_b128 v[66:69], v172 offset:4352
	ds_read_b128 v[70:73], v172 offset:4416
	s_waitcnt lgkmcnt(0)
	v_mfma_f32_16x16x32_bf16 v[58:61], v[58:61], v[66:69], 0
	ds_read_b128 v[66:69], v88 offset:33920
	ds_read_b128 v[74:77], v88 offset:33984
	s_waitcnt lgkmcnt(2)
	v_mfma_f32_16x16x32_bf16 v[58:61], v[62:65], v[70:73], v[58:61]
	ds_read_b128 v[62:65], v172 offset:4480
	ds_read_b128 v[70:73], v172 offset:4544
	s_waitcnt lgkmcnt(0)
	v_mfma_f32_16x16x32_bf16 v[58:61], v[66:69], v[62:65], v[58:61]
	v_cvt_pk_bf16_f32 v66, v10, v11
	v_cvt_pk_bf16_f32 v67, v12, v13
	v_cvt_pk_bf16_f32 v68, v2, v3
	s_waitcnt lgkmcnt(0)
	v_mfma_f32_16x16x32_bf16 v[58:61], v[74:77], v[70:73], v[58:61]
	v_cvt_pk_bf16_f32 v69, v4, v5
	v_cvt_pk_bf16_f32 v70, v30, v31
	v_cvt_pk_bf16_f32 v71, v32, v33
	v_cvt_pk_bf16_f32 v72, v22, v23
	v_cvt_pk_bf16_f32 v73, v24, v25
	v_cvt_pk_bf16_f32 v74, v6, v7
	s_nop 1
	v_cndmask_b32_e64 v58, v58, 0, s[30:31]
	v_cndmask_b32_e64 v60, v60, 0, s[36:37]
	v_cvt_pk_bf16_f32 v75, v8, v9
	v_cndmask_b32_e64 v59, 0, v59, s[34:35]
	v_cndmask_b32_e64 v61, v61, 0, s[38:39]
	v_cvt_pk_bf16_f32 v76, v18, v19
	v_cvt_pk_bf16_f32 v58, v58, v59
	v_cvt_pk_bf16_f32 v59, v60, v61
	ds_write_b64 v173, v[58:59] offset:2304
	s_waitcnt lgkmcnt(0)
	s_barrier
	ds_read_b64_tr_b16 v[62:63], v174
	ds_read_b64_tr_b16 v[64:65], v174 offset:1088
	ds_read_b64_tr_b16 v[58:59], v174 offset:8704
	ds_read_b64_tr_b16 v[60:61], v174 offset:9792
	ds_read2_b64 v[178:181], v142 offset1:4
	v_cvt_pk_bf16_f32 v77, v20, v21
	v_cvt_pk_bf16_f32 v78, v14, v15
	ds_read2_b64 v[182:185], v142 offset0:8 offset1:12
	s_waitcnt lgkmcnt(0)
	v_mfma_f32_16x16x32_bf16 v[178:181], v[66:69], v[178:181], 0
	v_cvt_pk_bf16_f32 v79, v16, v17
	ds_read2_b64 v[186:189], v142 offset0:16 offset1:20
	s_waitcnt lgkmcnt(1)
	v_mfma_f32_16x16x32_bf16 v[178:181], v[70:73], v[182:185], v[178:181]
	v_cvt_pk_bf16_f32 v80, v26, v27
	v_cvt_pk_bf16_f32 v81, v28, v29
	ds_read2_b64 v[182:185], v142 offset0:24 offset1:28
	s_waitcnt lgkmcnt(0)
	v_mfma_f32_16x16x32_bf16 v[178:181], v[74:77], v[186:189], v[178:181]
	ds_read_b128 v[186:189], v176
	ds_read_b128 v[190:193], v176 offset:64
	v_xor_b32_e32 v92, 16, v225
	s_waitcnt lgkmcnt(2)
	v_mfma_f32_16x16x32_bf16 v[180:183], v[78:81], v[182:185], v[178:181]
	v_cmp_lt_i32_e32 vcc, v92, v93
	s_waitcnt lgkmcnt(0)
	v_mfma_f32_16x16x32_bf16 v[184:187], v[62:65], v[186:189], 0
	v_cndmask_b32_e32 v92, v225, v92, vcc
	v_lshlrev_b32_e32 v177, 2, v92
	v_xor_b32_e32 v92, 32, v225
	s_waitcnt lgkmcnt(0)
	v_mfma_f32_16x16x32_bf16 v[184:187], v[58:61], v[190:193], v[184:187]
	v_cmp_lt_i32_e32 vcc, v92, v93
	s_nop 1
	v_cndmask_b32_e32 v92, v225, v92, vcc
	v_lshlrev_b32_e32 v178, 2, v92
	s_nop 2
	v_pk_add_f32 v[92:93], v[182:183], v[186:187]
	v_pk_add_f32 v[166:167], v[180:181], v[184:185]
	v_cvt_pk_bf16_f32 v181, v92, v93
	v_cvt_pk_bf16_f32 v182, v166, v167
	v_mul_f32_e32 v167, v167, v167
	v_mul_f32_e32 v93, v93, v93
	v_fmac_f32_e32 v167, v166, v166
	v_fmac_f32_e32 v93, v92, v92
	v_add_f32_e32 v93, v167, v93
	ds_bpermute_b32 v183, v177, v93
	v_mov_b32_e32 v92, v182
	v_mov_b32_e32 v167, v181
	s_waitcnt lgkmcnt(0)
	v_add_f32_e32 v179, v93, v183
	v_mov_b32_e32 v166, v92
	ds_bpermute_b32 v180, v178, v179
	v_add_u32_e32 v92, s52, v171
	v_ashrrev_i32_e32 v93, 31, v92
	v_lshlrev_b64 v[182:183], 11, v[92:93]
	v_lshl_add_u64 v[182:183], v[82:83], 0, v[182:183]
	flat_store_dwordx2 v[182:183], v[166:167]
	s_and_saveexec_b64 s[0:1], s[10:11]
	s_cbranch_execz .LBB0_564
	s_waitcnt lgkmcnt(0)
	v_add_f32_e32 v93, v179, v180
	ds_write_b32 v143, v93
; #define LAS __attribute__((address_space(3)))
; __device__ __forceinline__ unsigned pk2(float lo, float hi) { return f2bf(lo) | (f2bf(hi) << 16); }
; #define MFMA16(a, b, c) __builtin_amdgcn_mfma_f32_16x16x32_bf16((a), (b), (c), 0, 0, 0)
; template <int KIND, int MODE>
; __device__ __forceinline__ void scan_unit(Frame& F, int layer, int h, int vhalf, int grp) {
;     ...
;             for (int tt = 0; tt < 4; ++tt) { const int t = 16 * tt + li; f32x4 oi = (f32x4){0.f, 0.f, 0.f, 0.f}, oe = (f32x4){0.f, 0.f, 0.f, 0.f};
; #pragma unroll
;                 for (int ks = 0; ks < 2; ++ks) { const bf16x8 pb = *(const LAS bf16x8*)(PS + t * PST + 32 * ks + 8 * g); oi = MFMA16(vf[ks], pb, oi); }
; #pragma unroll
;                 for (int i = 0; i < NSL; ++i) { const u32x2 q0 = *(const LAS u32x2*)(QS + t * QST + 32 * i + 4 * g), q1 = *(const LAS u32x2*)(QS + t * QST + 32 * i + 16 + 4 * g);
;                     const bf16x8 qb = __builtin_bit_cast(bf16x8, ((u32x4){q0.x, q0.y, q1.x, q1.y})); oe = MFMA16(sf[i], qb, oe); }
;                 f32x4 o;
;                 if (KIND) { const float wi = X[128 + t]; float qn = wi * (((X[896 + t] + X[960 + t]) + (X[1024 + t] + X[1088 + t])) + ((X[1152 + t] + X[1216 + t]) + (X[1280 + t] + X[1344 + t])));
;                     qn += (X[640 + t] + X[704 + t]) + (X[768 + t] + X[832 + t]);
;                     const float inv = 1.0f / fmaxf(fabsf(qn), X[256 + t]); o = (oi + oe * wi) * inv; }
;                 else o = oi + oe;
;                 u32x2 ow; ow.x = pk2(o[0], o[1]); ow.y = pk2(o[2], o[3]); *(u32x2*)(yout + (size_t)(tb + t) * D) = ow;
;                 float sq = (o[0] * o[0] + o[1] * o[1]) + (o[2] * o[2] + o[3] * o[3]); sq += __shfl_xor(sq, 16); sq += __shfl_xor(sq, 32);
;                 if (g == 0) SSR[w * 64 + t] = sq;
;             }
.LBB0_564:
	s_or_b64 exec, exec, s[0:1]
	s_waitcnt lgkmcnt(0)
	ds_read2_b64 v[180:183], v144 offset1:4
	ds_read2_b64 v[184:187], v144 offset0:8 offset1:12
	s_waitcnt lgkmcnt(0)
	v_mfma_f32_16x16x32_bf16 v[180:183], v[66:69], v[180:183], 0
	v_mfma_f32_16x16x32_bf16 v[180:183], v[70:73], v[184:187], v[180:183]
	ds_read2_b64 v[184:187], v144 offset0:16 offset1:20
	s_waitcnt lgkmcnt(0)
	v_mfma_f32_16x16x32_bf16 v[180:183], v[74:77], v[184:187], v[180:183]
	ds_read2_b64 v[184:187], v144 offset0:24 offset1:28
	s_waitcnt lgkmcnt(0)
	v_mfma_f32_16x16x32_bf16 v[180:183], v[78:81], v[184:187], v[180:183]
	ds_read_b128 v[184:187], v176 offset:2304
	ds_read_b128 v[188:191], v176 offset:2368
	s_waitcnt lgkmcnt(0)
	v_mfma_f32_16x16x32_bf16 v[184:187], v[62:65], v[184:187], 0
	v_mfma_f32_16x16x32_bf16 v[184:187], v[58:61], v[188:191], v[184:187]
	s_nop 7
	v_pk_add_f32 v[166:167], v[182:183], v[186:187]
	v_pk_add_f32 v[180:181], v[180:181], v[184:185]
	v_mul_f32_e32 v184, v181, v181
	v_cvt_pk_bf16_f32 v182, v166, v167
	v_mul_f32_e32 v167, v167, v167
	v_fmac_f32_e32 v184, v180, v180
	v_fmac_f32_e32 v167, v166, v166
	v_cvt_pk_bf16_f32 v179, v180, v181
	v_mov_b32_e32 v180, v182
	v_add_f32_e32 v182, v184, v167
	ds_bpermute_b32 v183, v177, v182
	v_mov_b32_e32 v167, v180
	s_waitcnt lgkmcnt(0)
	v_add_f32_e32 v93, v182, v183
	v_mov_b32_e32 v166, v179
	ds_bpermute_b32 v179, v178, v93
	v_add_u32_e32 v180, 16, v92
	v_ashrrev_i32_e32 v181, 31, v180
	v_lshlrev_b64 v[180:181], 11, v[180:181]
	v_lshl_add_u64 v[180:181], v[82:83], 0, v[180:181]
	flat_store_dwordx2 v[180:181], v[166:167]
	s_and_saveexec_b64 s[0:1], s[10:11]
	s_cbranch_execz .LBB0_566
	s_waitcnt lgkmcnt(0)
	v_add_f32_e32 v93, v93, v179
	ds_write_b32 v143, v93 offset:64
.LBB0_566:
	s_or_b64 exec, exec, s[0:1]
	ds_read2_b64 v[180:183], v145 offset1:4
	ds_read2_b64 v[184:187], v145 offset0:8 offset1:12
	s_waitcnt lgkmcnt(0)
	v_mfma_f32_16x16x32_bf16 v[180:183], v[66:69], v[180:183], 0
	v_mfma_f32_16x16x32_bf16 v[180:183], v[70:73], v[184:187], v[180:183]
	ds_read2_b64 v[184:187], v145 offset0:16 offset1:20
	s_waitcnt lgkmcnt(0)
	v_mfma_f32_16x16x32_bf16 v[180:183], v[74:77], v[184:187], v[180:183]
	ds_read2_b64 v[184:187], v145 offset0:24 offset1:28
	s_waitcnt lgkmcnt(0)
	v_mfma_f32_16x16x32_bf16 v[180:183], v[78:81], v[184:187], v[180:183]
	ds_read_b128 v[184:187], v176 offset:4608
	ds_read_b128 v[188:191], v176 offset:4672
	s_waitcnt lgkmcnt(0)
	v_mfma_f32_16x16x32_bf16 v[184:187], v[62:65], v[184:187], 0
	v_mfma_f32_16x16x32_bf16 v[184:187], v[58:61], v[188:191], v[184:187]
	s_nop 7
	v_pk_add_f32 v[166:167], v[182:183], v[186:187]
	v_pk_add_f32 v[180:181], v[180:181], v[184:185]
	v_mul_f32_e32 v184, v181, v181
	v_cvt_pk_bf16_f32 v182, v166, v167
	v_mul_f32_e32 v167, v167, v167
	v_fmac_f32_e32 v184, v180, v180
	v_fmac_f32_e32 v167, v166, v166
	v_cvt_pk_bf16_f32 v179, v180, v181
	v_mov_b32_e32 v180, v182
	v_add_f32_e32 v182, v184, v167
	ds_bpermute_b32 v183, v177, v182
	v_mov_b32_e32 v167, v180
	s_waitcnt lgkmcnt(0)
	v_add_f32_e32 v93, v182, v183
	v_mov_b32_e32 v166, v179
	ds_bpermute_b32 v179, v178, v93
	v_add_u32_e32 v180, 32, v92
	v_ashrrev_i32_e32 v181, 31, v180
	v_lshlrev_b64 v[180:181], 11, v[180:181]
	v_lshl_add_u64 v[180:181], v[82:83], 0, v[180:181]
	flat_store_dwordx2 v[180:181], v[166:167]
	s_and_saveexec_b64 s[0:1], s[10:11]
	s_cbranch_execz .LBB0_568
	s_waitcnt lgkmcnt(0)
	v_add_f32_e32 v93, v93, v179
	ds_write_b32 v143, v93 offset:128
.LBB0_568:
	s_or_b64 exec, exec, s[0:1]
	ds_read2_b64 v[180:183], v147 offset1:4
	s_waitcnt lgkmcnt(0)
	v_mfma_f32_16x16x32_bf16 v[66:69], v[66:69], v[180:183], 0
	ds_read2_b64 v[180:183], v147 offset0:8 offset1:12
	s_waitcnt lgkmcnt(0)
	v_mfma_f32_16x16x32_bf16 v[66:69], v[70:73], v[180:183], v[66:69]
	ds_read2_b64 v[70:73], v147 offset0:16 offset1:20
	s_waitcnt lgkmcnt(0)
	v_mfma_f32_16x16x32_bf16 v[66:69], v[74:77], v[70:73], v[66:69]
	ds_read2_b64 v[70:73], v147 offset0:24 offset1:28
	s_waitcnt lgkmcnt(0)
	v_mfma_f32_16x16x32_bf16 v[66:69], v[78:81], v[70:73], v[66:69]
	ds_read_b128 v[70:73], v176 offset:6912
	ds_read_b128 v[74:77], v176 offset:6976
	s_waitcnt lgkmcnt(0)
	v_mfma_f32_16x16x32_bf16 v[70:73], v[62:65], v[70:73], 0
	v_mfma_f32_16x16x32_bf16 v[70:73], v[58:61], v[74:77], v[70:73]
	s_nop 7
	v_pk_add_f32 v[68:69], v[68:69], v[72:73]
	v_pk_add_f32 v[66:67], v[66:67], v[70:71]
	v_mul_f32_e32 v74, v67, v67
	v_cvt_pk_bf16_f32 v72, v68, v69
	v_mul_f32_e32 v69, v69, v69
	v_fmac_f32_e32 v74, v66, v66
	v_fmac_f32_e32 v69, v68, v68
	v_cvt_pk_bf16_f32 v71, v66, v67
	v_mov_b32_e32 v66, v72
	v_add_f32_e32 v72, v74, v69
	ds_bpermute_b32 v73, v177, v72
	v_mov_b32_e32 v69, v66
	s_waitcnt lgkmcnt(0)
	v_add_f32_e32 v66, v72, v73
	v_mov_b32_e32 v68, v71
	ds_bpermute_b32 v67, v178, v66
	v_add_u32_e32 v70, 48, v92
	v_ashrrev_i32_e32 v71, 31, v70
	v_lshlrev_b64 v[70:71], 11, v[70:71]
	v_lshl_add_u64 v[70:71], v[82:83], 0, v[70:71]
	flat_store_dwordx2 v[70:71], v[68:69]
	s_and_saveexec_b64 s[0:1], s[10:11]
	s_cbranch_execz .LBB0_570
	s_waitcnt lgkmcnt(0)
	v_add_f32_e32 v66, v66, v67
	ds_write_b32 v143, v66 offset:192
